# kernel start: silu(c) staging loop unrolled with its eight cold loads issued together
# speedup vs baseline: 1.0315x; 1.0011x over previous
.LBB0_5:
	s_or_b64 exec, exec, s[4:5]
	v_mov_b32_e32 v8, v226
	s_mov_b64 s[10:11], s[0:1]
	s_mov_b64 s[2:3], s[0:1]
	s_load_dwordx2 s[14:15], s[2:3], 0x10
	s_mov_b64 s[2:3], s[0:1]
	s_load_dwordx2 s[18:19], s[2:3], 0x18
	s_mov_b64 s[2:3], s[0:1]
	s_load_dwordx2 s[8:9], s[2:3], 0x68
	s_mov_b64 s[2:3], s[0:1]
	s_load_dwordx2 s[6:7], s[2:3], 0xa0
	s_mov_b64 s[2:3], s[0:1]
	s_load_dwordx2 s[20:21], s[2:3], 0xa0
	s_movk_i32 s2, 0x1000
	v_readfirstlane_b32 s40, v8
	v_cmp_gt_i32_e32 vcc, s2, v8
	v_ashrrev_i32_e32 v9, 31, v8
	s_and_saveexec_b64 s[4:5], vcc
	s_cbranch_execz .LBB0_8
	s_load_dwordx2 s[2:3], s[10:11], 0x8
	v_lshl_add_u32 v2, v8, 2, 0
	v_add_u32_e32 v4, 0x18000, v2
	s_waitcnt lgkmcnt(0)
	v_lshl_add_u64 v[2:3], v[8:9], 2, s[2:3]
	s_mov_b64 s[24:25], 0x1000
	v_lshl_add_u64 v[240:241], v[2:3], 0, s[24:25]
	s_mov_b64 s[24:25], 0x2000
	v_lshl_add_u64 v[242:243], v[2:3], 0, s[24:25]
	s_mov_b64 s[24:25], 0x3000
	v_lshl_add_u64 v[244:245], v[2:3], 0, s[24:25]
	global_load_dword v246, v[2:3], off
	global_load_dword v247, v[2:3], off offset:2048
	global_load_dword v248, v[240:241], off
	global_load_dword v249, v[240:241], off offset:2048
	global_load_dword v250, v[242:243], off
	global_load_dword v251, v[242:243], off offset:2048
	global_load_dword v252, v[244:245], off
	global_load_dword v254, v[244:245], off offset:2048
	s_waitcnt vmcnt(7)
	v_mul_f32_e32 v6, 0xbfb8aa3b, v246
	v_exp_f32_e32 v6, v6
	s_nop 0
	v_add_f32_e32 v6, 1.0, v6
	v_div_scale_f32 v7, s[16:17], v6, v6, v246
	v_rcp_f32_e32 v10, v7
	v_div_scale_f32 v11, vcc, v246, v6, v246
	v_fma_f32 v12, -v7, v10, 1.0
	v_fmac_f32_e32 v10, v12, v10
	v_mul_f32_e32 v12, v11, v10
	v_fma_f32 v13, -v7, v12, v11
	v_fmac_f32_e32 v12, v13, v10
	v_fma_f32 v7, -v7, v12, v11
	v_div_fmas_f32 v7, v7, v10, v12
	v_div_fixup_f32 v5, v7, v6, v246
	ds_write_b32 v4, v5
	s_waitcnt vmcnt(6)
	v_mul_f32_e32 v6, 0xbfb8aa3b, v247
	v_exp_f32_e32 v6, v6
	s_nop 0
	v_add_f32_e32 v6, 1.0, v6
	v_div_scale_f32 v7, s[16:17], v6, v6, v247
	v_rcp_f32_e32 v10, v7
	v_div_scale_f32 v11, vcc, v247, v6, v247
	v_fma_f32 v12, -v7, v10, 1.0
	v_fmac_f32_e32 v10, v12, v10
	v_mul_f32_e32 v12, v11, v10
	v_fma_f32 v13, -v7, v12, v11
	v_fmac_f32_e32 v12, v13, v10
	v_fma_f32 v7, -v7, v12, v11
	v_div_fmas_f32 v7, v7, v10, v12
	v_div_fixup_f32 v5, v7, v6, v247
	ds_write_b32 v4, v5 offset:2048
	s_waitcnt vmcnt(5)
	v_mul_f32_e32 v6, 0xbfb8aa3b, v248
	v_exp_f32_e32 v6, v6
	s_nop 0
	v_add_f32_e32 v6, 1.0, v6
	v_div_scale_f32 v7, s[16:17], v6, v6, v248
	v_rcp_f32_e32 v10, v7
	v_div_scale_f32 v11, vcc, v248, v6, v248
	v_fma_f32 v12, -v7, v10, 1.0
	v_fmac_f32_e32 v10, v12, v10
	v_mul_f32_e32 v12, v11, v10
	v_fma_f32 v13, -v7, v12, v11
	v_fmac_f32_e32 v12, v13, v10
	v_fma_f32 v7, -v7, v12, v11
	v_div_fmas_f32 v7, v7, v10, v12
	v_div_fixup_f32 v5, v7, v6, v248
	ds_write_b32 v4, v5 offset:4096
	s_waitcnt vmcnt(4)
	v_mul_f32_e32 v6, 0xbfb8aa3b, v249
	v_exp_f32_e32 v6, v6
	s_nop 0
	v_add_f32_e32 v6, 1.0, v6
	v_div_scale_f32 v7, s[16:17], v6, v6, v249
	v_rcp_f32_e32 v10, v7
	v_div_scale_f32 v11, vcc, v249, v6, v249
	v_fma_f32 v12, -v7, v10, 1.0
	v_fmac_f32_e32 v10, v12, v10
	v_mul_f32_e32 v12, v11, v10
	v_fma_f32 v13, -v7, v12, v11
	v_fmac_f32_e32 v12, v13, v10
	v_fma_f32 v7, -v7, v12, v11
	v_div_fmas_f32 v7, v7, v10, v12
	v_div_fixup_f32 v5, v7, v6, v249
	ds_write_b32 v4, v5 offset:6144
	s_waitcnt vmcnt(3)
	v_mul_f32_e32 v6, 0xbfb8aa3b, v250
	v_exp_f32_e32 v6, v6
	s_nop 0
	v_add_f32_e32 v6, 1.0, v6
	v_div_scale_f32 v7, s[16:17], v6, v6, v250
	v_rcp_f32_e32 v10, v7
	v_div_scale_f32 v11, vcc, v250, v6, v250
	v_fma_f32 v12, -v7, v10, 1.0
	v_fmac_f32_e32 v10, v12, v10
	v_mul_f32_e32 v12, v11, v10
	v_fma_f32 v13, -v7, v12, v11
	v_fmac_f32_e32 v12, v13, v10
	v_fma_f32 v7, -v7, v12, v11
	v_div_fmas_f32 v7, v7, v10, v12
	v_div_fixup_f32 v5, v7, v6, v250
	ds_write_b32 v4, v5 offset:8192
	s_waitcnt vmcnt(2)
	v_mul_f32_e32 v6, 0xbfb8aa3b, v251
	v_exp_f32_e32 v6, v6
	s_nop 0
	v_add_f32_e32 v6, 1.0, v6
	v_div_scale_f32 v7, s[16:17], v6, v6, v251
	v_rcp_f32_e32 v10, v7
	v_div_scale_f32 v11, vcc, v251, v6, v251
	v_fma_f32 v12, -v7, v10, 1.0
	v_fmac_f32_e32 v10, v12, v10
	v_mul_f32_e32 v12, v11, v10
	v_fma_f32 v13, -v7, v12, v11
	v_fmac_f32_e32 v12, v13, v10
	v_fma_f32 v7, -v7, v12, v11
	v_div_fmas_f32 v7, v7, v10, v12
	v_div_fixup_f32 v5, v7, v6, v251
	ds_write_b32 v4, v5 offset:10240
	s_waitcnt vmcnt(1)
	v_mul_f32_e32 v6, 0xbfb8aa3b, v252
	v_exp_f32_e32 v6, v6
	s_nop 0
	v_add_f32_e32 v6, 1.0, v6
	v_div_scale_f32 v7, s[16:17], v6, v6, v252
	v_rcp_f32_e32 v10, v7
	v_div_scale_f32 v11, vcc, v252, v6, v252
	v_fma_f32 v12, -v7, v10, 1.0
	v_fmac_f32_e32 v10, v12, v10
	v_mul_f32_e32 v12, v11, v10
	v_fma_f32 v13, -v7, v12, v11
	v_fmac_f32_e32 v12, v13, v10
	v_fma_f32 v7, -v7, v12, v11
	v_div_fmas_f32 v7, v7, v10, v12
	v_div_fixup_f32 v5, v7, v6, v252
	ds_write_b32 v4, v5 offset:12288
	s_waitcnt vmcnt(0)
	v_mul_f32_e32 v6, 0xbfb8aa3b, v254
	v_exp_f32_e32 v6, v6
	s_nop 0
	v_add_f32_e32 v6, 1.0, v6
	v_div_scale_f32 v7, s[16:17], v6, v6, v254
	v_rcp_f32_e32 v10, v7
	v_div_scale_f32 v11, vcc, v254, v6, v254
	v_fma_f32 v12, -v7, v10, 1.0
	v_fmac_f32_e32 v10, v12, v10
	v_mul_f32_e32 v12, v11, v10
	v_fma_f32 v13, -v7, v12, v11
	v_fmac_f32_e32 v12, v13, v10
	v_fma_f32 v7, -v7, v12, v11
	v_div_fmas_f32 v7, v7, v10, v12
	v_div_fixup_f32 v5, v7, v6, v254
	ds_write_b32 v4, v5 offset:14336
